# hyena long conv: software-pipelined inner loop (next lag's LDS fragments loaded during this lag's MFMAs)
# speedup vs baseline: 1.0052x; 1.0014x over previous
; #define LAS __attribute__((address_space(3)))
; DI void hyena_unit(const Inputs& in, int l, unsigned char* ws, int half, int c, LAS unsigned char* lds, int tid) {
;     ...
;     const LAS unsigned char* Zb = Zl + (size_t)b0 * ZSP * 2;
;     const int zstep = ZSP * 2;
;     int s0 = L - 32 * dlo - i32 + 8 * g;
;     const LAS unsigned char* zp0 = Zb + ((32 + a0 + i32 - dlo) * 40 + 8 * g) * 2;
;     ...
;     for (int d = dlo; d <= dhi; ++d) {
; #pragma unroll
;         for (int jh = 0; jh < 2; ++jh) { const bf16x8 a = HY_A(jh);
;             acc0 = __builtin_amdgcn_mfma_f32_32x32x16_bf16(a, HY_B(0, jh), acc0, 0, 0, 0);
;             acc1 = __builtin_amdgcn_mfma_f32_32x32x16_bf16(a, HY_B(1, jh), acc1, 0, 0, 0); }
;         s0 -= 32; zp0 -= 80;
;     }
.LBB0_660:
	v_lshlrev_b32_e32 v46, 1, v32
	v_subrev_u32_e32 v47, 32, v46
	v_and_b32_e32 v47, -4, v47
	v_add_u32_e32 v33, s42, v104
	v_add_u32_e32 v47, v91, v47
	v_and_b32_e32 v48, -4, v46
	v_add_u32_e32 v48, v91, v48
	v_add_u32_e32 v50, s42, v105
	ds_read_b128 v[142:145], v33
	ds_read2_b32 v[134:135], v47 offset1:1
	ds_read2_b32 v[136:137], v47 offset0:2 offset1:3
	ds_read_b128 v[150:153], v50
	ds_read_b128 v[146:149], v33 offset:32
	ds_read2_b32 v[138:139], v48 offset1:1
	ds_read2_b32 v[140:141], v48 offset0:2 offset1:3
	ds_read_b128 v[154:157], v50 offset:32
	s_addk_i32 s42, 0xffb0
	v_subrev_u32_e32 v32, 32, v32
.Lhy_loop:
	v_lshlrev_b32_e32 v46, 1, v32
	v_subrev_u32_e32 v47, 32, v46
	v_and_b32_e32 v47, -4, v47
	v_add_u32_e32 v33, s42, v104
	v_add_u32_e32 v47, v91, v47
	v_and_b32_e32 v48, -4, v46
	v_add_u32_e32 v48, v91, v48
	v_add_u32_e32 v50, s42, v105
	ds_read_b128 v[166:169], v33
	ds_read2_b32 v[158:159], v47 offset1:1
	ds_read2_b32 v[160:161], v47 offset0:2 offset1:3
	ds_read_b128 v[34:37], v50
	ds_read_b128 v[170:173], v33 offset:32
	ds_read2_b32 v[162:163], v48 offset1:1
	ds_read2_b32 v[164:165], v48 offset0:2 offset1:3
	ds_read_b128 v[42:45], v50 offset:32
	s_addk_i32 s42, 0xffb0
	v_subrev_u32_e32 v32, 32, v32
	s_waitcnt lgkmcnt(8)
	v_mfma_f32_32x32x16_bf16 v[16:31], v[134:137], v[142:145], v[16:31]
	v_mfma_f32_32x32x16_bf16 v[0:15], v[134:137], v[150:153], v[0:15]
	v_mfma_f32_32x32x16_bf16 v[16:31], v[138:141], v[146:149], v[16:31]
	v_mfma_f32_32x32x16_bf16 v[0:15], v[138:141], v[154:157], v[0:15]
	s_add_i32 s74, s81, s42
	s_cmp_lg_u32 s74, 0xffffffb0
	s_cbranch_scc0 .Lhy_done
	v_lshlrev_b32_e32 v46, 1, v32
	v_subrev_u32_e32 v47, 32, v46
	v_and_b32_e32 v47, -4, v47
	v_add_u32_e32 v33, s42, v104
	v_add_u32_e32 v47, v91, v47
	v_and_b32_e32 v48, -4, v46
	v_add_u32_e32 v48, v91, v48
	v_add_u32_e32 v50, s42, v105
	ds_read_b128 v[142:145], v33
	ds_read2_b32 v[134:135], v47 offset1:1
	ds_read2_b32 v[136:137], v47 offset0:2 offset1:3
	ds_read_b128 v[150:153], v50
	ds_read_b128 v[146:149], v33 offset:32
	ds_read2_b32 v[138:139], v48 offset1:1
	ds_read2_b32 v[140:141], v48 offset0:2 offset1:3
	ds_read_b128 v[154:157], v50 offset:32
	s_addk_i32 s42, 0xffb0
	v_subrev_u32_e32 v32, 32, v32
	s_waitcnt lgkmcnt(8)
	v_mfma_f32_32x32x16_bf16 v[16:31], v[158:161], v[166:169], v[16:31]
	v_mfma_f32_32x32x16_bf16 v[0:15], v[158:161], v[34:37], v[0:15]
	v_mfma_f32_32x32x16_bf16 v[16:31], v[162:165], v[170:173], v[16:31]
	v_mfma_f32_32x32x16_bf16 v[0:15], v[162:165], v[42:45], v[0:15]
	s_add_i32 s74, s81, s42
	s_cmp_lg_u32 s74, 0xffffffb0
	s_cbranch_scc1 .Lhy_loop
.Lhy_done:
	s_waitcnt lgkmcnt(0)
	s_branch .LBB0_617
